# norm loop: second row's loads issued before waiting on the first row (counted vmcnt(4)), both rows in flight
# baseline (speedup 1.0000x reference)
; #pragma unroll
;     for (int j = 0; j < 4; ++j) { r.v[j] = src ? ((const f32x4*)src)[lane + 64 * j] : (f32x4){0.f, 0.f, 0.f, 0.f}; r.ss += (r.v[j].x * r.v[j].x + r.v[j].y * r.v[j].y) + (r.v[j].z * r.v[j].z + r.v[j].w * r.v[j].w); }
;     return r; }
; DEVQ void prep_phase(const Params& P, LAS unsigned char* lds, int gw, int ngw, int wave, int lane) {
;     ...
;     for (int m = 2 * gw; m < TPAD; m += 2 * ngw) {
;         const RowV ra = row_load(h0_src(P, m), lane), rb = row_load(h0_src(P, m + 1), lane);
;         row_finish(ra, P.in[3], U + (size_t)m * D, H + (size_t)m * D, P.in[19], lane);
;         row_finish(rb, P.in[3], U + (size_t)(m + 1) * D, H + (size_t)(m + 1) * D, P.in[19], lane);
.LBB0_183:
	v_lshl_add_u64 v[0:1], s[18:19], 0, v[42:43]
	v_add_co_u32_e32 v2, vcc, 0x3200000, v0
	s_addk_i32 s4, 0x780
	s_nop 0
	v_addc_co_u32_e32 v3, vcc, 0, v1, vcc
	global_load_dwordx4 v[28:31], v[2:3], off
	global_load_dwordx4 v[24:27], v[2:3], off offset:1024
	global_load_dwordx4 v[20:23], v[2:3], off offset:2048
	global_load_dwordx4 v[16:19], v[2:3], off offset:3072
	v_add_co_u32_e32 v0, vcc, s30, v0
	v_lshl_add_u64 v[42:43], v[42:43], 0, s[14:15]
	s_nop 0
	v_addc_co_u32_e32 v1, vcc, 0, v1, vcc
	s_cmp_gt_i32 s4, 0x987f
	global_load_dwordx4 v[12:15], v[0:1], off
	global_load_dwordx4 v[8:11], v[0:1], off offset:1024
	global_load_dwordx4 v[4:7], v[0:1], off offset:2048
	global_load_dwordx4 v[0:3], v[0:1], off offset:3072
	s_waitcnt vmcnt(4) lgkmcnt(0)
	v_mul_f32_e32 v80, v29, v29
	v_mul_f32_e32 v81, v31, v31
	v_fmac_f32_e32 v80, v28, v28
	v_fmac_f32_e32 v81, v30, v30
	v_add_f32_e32 v80, v80, v81
	v_mul_f32_e32 v81, v25, v25
	v_mul_f32_e32 v82, v27, v27
	v_fmac_f32_e32 v81, v24, v24
	v_fmac_f32_e32 v82, v26, v26
	v_add_f32_e32 v81, v81, v82
	v_add_f32_e32 v80, v80, v81
	v_mul_f32_e32 v81, v21, v21
	v_mul_f32_e32 v82, v23, v23
	v_fmac_f32_e32 v81, v20, v20
	v_fmac_f32_e32 v82, v22, v22
	v_add_f32_e32 v81, v81, v82
	v_add_f32_e32 v80, v80, v81
	v_mul_f32_e32 v81, v17, v17
	v_mul_f32_e32 v82, v19, v19
	v_fmac_f32_e32 v81, v16, v16
	v_fmac_f32_e32 v82, v18, v18
	v_add_f32_e32 v81, v81, v82
	v_add_f32_e32 v51, v80, v81
	s_waitcnt vmcnt(0)
	v_mul_f32_e32 v50, v13, v13
	v_mul_f32_e32 v52, v15, v15
	v_fmac_f32_e32 v50, v12, v12
	v_fmac_f32_e32 v52, v14, v14
	v_add_f32_e32 v50, v50, v52
	v_mul_f32_e32 v52, v9, v9
	v_mul_f32_e32 v53, v11, v11
	v_fmac_f32_e32 v52, v8, v8
	v_fmac_f32_e32 v53, v10, v10
	v_add_f32_e32 v52, v52, v53
	v_add_f32_e32 v50, v50, v52
	v_mul_f32_e32 v52, v5, v5
	v_mul_f32_e32 v53, v7, v7
	v_fmac_f32_e32 v52, v4, v4
	v_fmac_f32_e32 v53, v6, v6
	v_add_f32_e32 v52, v52, v53
	v_add_f32_e32 v50, v50, v52
	v_mul_f32_e32 v52, v1, v1
	v_mul_f32_e32 v53, v3, v3
	v_fmac_f32_e32 v52, v0, v0
	v_fmac_f32_e32 v53, v2, v2
	v_add_f32_e32 v52, v52, v53
	v_add_f32_e32 v50, v50, v52
	ds_bpermute_b32 v52, v44, v51
	s_waitcnt lgkmcnt(0)
	v_add_f32_e32 v51, v51, v52
	ds_bpermute_b32 v52, v45, v51
	s_waitcnt lgkmcnt(0)
	v_add_f32_e32 v51, v51, v52
	ds_bpermute_b32 v52, v46, v51
	s_waitcnt lgkmcnt(0)
	v_add_f32_e32 v51, v51, v52
	ds_bpermute_b32 v52, v47, v51
	s_waitcnt lgkmcnt(0)
	v_add_f32_e32 v51, v51, v52
	ds_bpermute_b32 v52, v48, v51
	s_waitcnt lgkmcnt(0)
	v_add_f32_e32 v51, v51, v52
	ds_bpermute_b32 v52, v49, v51
	s_waitcnt lgkmcnt(0)
	v_add_f32_e32 v51, v51, v52
	v_fmamk_f32 v51, v51, 0x3a800000, v178
	v_cmp_gt_f32_e32 vcc, s28, v51
	v_mul_f32_e32 v52, 0x4f800000, v51
	s_nop 0
	v_cndmask_b32_e32 v51, v51, v52, vcc
	v_sqrt_f32_e32 v52, v51
	s_nop 0
	v_add_u32_e32 v53, -1, v52
	v_fma_f32 v54, -v53, v52, v51
	v_cmp_ge_f32_e64 s[0:1], 0, v54
	v_add_u32_e32 v54, 1, v52
	s_nop 0
	v_cndmask_b32_e64 v53, v52, v53, s[0:1]
	v_fma_f32 v52, -v54, v52, v51
	v_cmp_lt_f32_e64 s[0:1], 0, v52
	s_nop 1
	v_cndmask_b32_e64 v52, v53, v54, s[0:1]
	v_mul_f32_e32 v53, 0x37800000, v52
	v_cndmask_b32_e32 v52, v52, v53, vcc
	v_cmp_class_f32_e32 vcc, v51, v179
	s_nop 1
	v_cndmask_b32_e32 v51, v52, v51, vcc
	v_div_scale_f32 v52, s[0:1], v51, v51, 1.0
	v_rcp_f32_e32 v53, v52
	s_nop 0
	v_fma_f32 v54, -v52, v53, 1.0
	v_fmac_f32_e32 v53, v54, v53
	v_div_scale_f32 v54, vcc, 1.0, v51, 1.0
	v_mul_f32_e32 v55, v54, v53
	v_fma_f32 v56, -v52, v55, v54
	v_fmac_f32_e32 v55, v56, v53
	v_fma_f32 v52, -v52, v55, v54
	v_div_fmas_f32 v52, v52, v53, v55
	v_div_fixup_f32 v51, v52, v51, 1.0
	v_mul_f32_e32 v28, v28, v51
	v_mul_f32_e32 v29, v29, v51
	v_mul_f32_e32 v24, v24, v51
	v_mul_f32_e32 v25, v25, v51
	v_mul_f32_e32 v20, v20, v51
	v_mul_f32_e32 v21, v21, v51
	v_mul_f32_e32 v16, v16, v51
	v_mul_f32_e32 v17, v17, v51
	v_mul_f32_e32 v28, v64, v28
	v_mul_f32_e32 v29, v65, v29
	v_bfe_u32 v52, v28, 16, 1
	v_add3_u32 v28, v28, v52, s60
	v_bfe_u32 v52, v29, 16, 1
	v_lshrrev_b32_e32 v28, 16, v28
	v_add3_u32 v29, v29, v52, s60
	v_and_or_b32 v52, v29, s61, v28
	v_mul_f32_e32 v28, v30, v51
	v_mul_f32_e32 v28, v66, v28
	v_mul_f32_e32 v29, v31, v51
	v_mul_f32_e32 v29, v67, v29
	v_bfe_u32 v30, v28, 16, 1
	v_add3_u32 v28, v28, v30, s60
	v_bfe_u32 v30, v29, 16, 1
	v_lshrrev_b32_e32 v28, 16, v28
	v_add3_u32 v29, v29, v30, s60
	v_and_or_b32 v53, v29, s61, v28
	v_lshl_add_u64 v[28:29], s[18:19], 0, v[40:41]
	v_add_co_u32_e32 v28, vcc, s31, v28
	s_nop 1
	v_addc_co_u32_e32 v29, vcc, 0, v29, vcc
	flat_store_dwordx2 v[28:29], v[52:53]
	v_mul_f32_e32 v24, v68, v24
	v_mul_f32_e32 v25, v69, v25
	v_bfe_u32 v30, v24, 16, 1
	v_add3_u32 v24, v24, v30, s60
	v_bfe_u32 v30, v25, 16, 1
	v_lshrrev_b32_e32 v24, 16, v24
	v_add3_u32 v25, v25, v30, s60
	v_and_or_b32 v24, v25, s61, v24
	v_mul_f32_e32 v25, v26, v51
	v_mul_f32_e32 v25, v70, v25
	v_mul_f32_e32 v26, v27, v51
	v_mul_f32_e32 v26, v71, v26
	v_bfe_u32 v27, v25, 16, 1
	v_add3_u32 v25, v25, v27, s60
	v_bfe_u32 v27, v26, 16, 1
	v_lshrrev_b32_e32 v25, 16, v25
	v_add3_u32 v26, v26, v27, s60
	v_and_or_b32 v25, v26, s61, v25
	flat_store_dwordx2 v[28:29], v[24:25] offset:512
	v_mul_f32_e32 v20, v72, v20
	v_mul_f32_e32 v21, v73, v21
	v_bfe_u32 v24, v20, 16, 1
	v_add3_u32 v20, v20, v24, s60
	v_bfe_u32 v24, v21, 16, 1
	v_lshrrev_b32_e32 v20, 16, v20
	v_add3_u32 v21, v21, v24, s60
	v_and_or_b32 v20, v21, s61, v20
	v_mul_f32_e32 v21, v22, v51
	v_mul_f32_e32 v21, v74, v21
	v_mul_f32_e32 v22, v23, v51
	v_mul_f32_e32 v22, v75, v22
	v_bfe_u32 v23, v21, 16, 1
	v_add3_u32 v21, v21, v23, s60
	v_bfe_u32 v23, v22, 16, 1
	v_lshrrev_b32_e32 v21, 16, v21
	v_add3_u32 v22, v22, v23, s60
	v_and_or_b32 v21, v22, s61, v21
	flat_store_dwordx2 v[28:29], v[20:21] offset:1024
	v_mul_f32_e32 v16, v16, v76
	v_mul_f32_e32 v17, v17, v77
	v_bfe_u32 v20, v16, 16, 1
	v_add3_u32 v16, v16, v20, s60
	v_bfe_u32 v20, v17, 16, 1
	v_lshrrev_b32_e32 v16, 16, v16
	v_add3_u32 v17, v17, v20, s60
	v_and_or_b32 v16, v17, s61, v16
	v_mul_f32_e32 v17, v18, v51
	v_mul_f32_e32 v17, v17, v78
	v_mul_f32_e32 v18, v19, v51
	v_mul_f32_e32 v18, v18, v79
	v_bfe_u32 v19, v17, 16, 1
	v_add3_u32 v17, v17, v19, s60
	v_bfe_u32 v19, v18, 16, 1
	v_lshrrev_b32_e32 v17, 16, v17
	v_add3_u32 v18, v18, v19, s60
	v_and_or_b32 v17, v18, s61, v17
	flat_store_dwordx2 v[28:29], v[16:17] offset:1536
	ds_bpermute_b32 v16, v44, v50
	s_waitcnt lgkmcnt(0)
; DEVQ unsigned pk2(float lo, float hi) { return f2bf(lo) | (f2bf(hi) << 16); }
; DEVQ void row_finish(const RowV& r, const float* g, bf16* urow, float* hcopy, const float* hbias, int lane) {
;     const float rstd = 1.0f / sqrtf(wave_sum(r.ss) * (1.0f / D) + RMS_EPS);
; #pragma unroll
;     for (int j = 0; j < 4; ++j) { const f32x4 gv = ((const f32x4*)g)[lane + 64 * j];
;         if (hcopy) ((f32x4*)hcopy)[lane + 64 * j] = r.v[j] + ((const f32x4*)hbias)[lane + 64 * j];
;         ((unsigned long long*)urow)[lane + 64 * j] = (unsigned long long)pk2(r.v[j].x * rstd * gv.x, r.v[j].y * rstd * gv.y) | ((unsigned long long)pk2(r.v[j].z * rstd * gv.z, r.v[j].w * rstd * gv.w) << 32); }
; }
	v_add_f32_e32 v16, v50, v16
	ds_bpermute_b32 v17, v45, v16
	s_waitcnt lgkmcnt(0)
	v_add_f32_e32 v16, v16, v17
	ds_bpermute_b32 v17, v46, v16
	s_waitcnt lgkmcnt(0)
	v_add_f32_e32 v16, v16, v17
	ds_bpermute_b32 v17, v47, v16
	s_waitcnt lgkmcnt(0)
	v_add_f32_e32 v16, v16, v17
	ds_bpermute_b32 v17, v48, v16
	s_waitcnt lgkmcnt(0)
	v_add_f32_e32 v16, v16, v17
	ds_bpermute_b32 v17, v49, v16
	s_waitcnt lgkmcnt(0)
	v_add_f32_e32 v16, v16, v17
	v_fmamk_f32 v16, v16, 0x3a800000, v178
	v_cmp_gt_f32_e32 vcc, s28, v16
	v_mul_f32_e32 v17, 0x4f800000, v16
	s_nop 0
	v_cndmask_b32_e32 v16, v16, v17, vcc
	v_sqrt_f32_e32 v17, v16
	s_nop 0
	v_add_u32_e32 v18, -1, v17
	v_fma_f32 v19, -v18, v17, v16
	v_cmp_ge_f32_e64 s[0:1], 0, v19
	v_add_u32_e32 v19, 1, v17
	s_nop 0
	v_cndmask_b32_e64 v18, v17, v18, s[0:1]
	v_fma_f32 v17, -v19, v17, v16
	v_cmp_lt_f32_e64 s[0:1], 0, v17
	s_nop 1
	v_cndmask_b32_e64 v17, v18, v19, s[0:1]
	v_mul_f32_e32 v18, 0x37800000, v17
	v_cndmask_b32_e32 v17, v17, v18, vcc
	v_cmp_class_f32_e32 vcc, v16, v179
	s_nop 1
	v_cndmask_b32_e32 v16, v17, v16, vcc
	v_div_scale_f32 v17, s[0:1], v16, v16, 1.0
	v_rcp_f32_e32 v18, v17
	s_mov_b64 s[0:1], 0x3c0000
	v_lshl_add_u64 v[40:41], v[40:41], 0, s[0:1]
	v_fma_f32 v19, -v17, v18, 1.0
	v_fmac_f32_e32 v18, v19, v18
	v_div_scale_f32 v19, vcc, 1.0, v16, 1.0
	v_mul_f32_e32 v20, v19, v18
	v_fma_f32 v21, -v17, v20, v19
	v_fmac_f32_e32 v20, v21, v18
	v_fma_f32 v17, -v17, v20, v19
	v_div_fmas_f32 v17, v17, v18, v20
	v_div_fixup_f32 v16, v17, v16, 1.0
	v_mul_f32_e32 v12, v12, v16
	v_mul_f32_e32 v13, v13, v16
	v_mul_f32_e32 v8, v8, v16
	v_mul_f32_e32 v9, v9, v16
	v_mul_f32_e32 v4, v4, v16
	v_mul_f32_e32 v5, v5, v16
	v_mul_f32_e32 v0, v0, v16
	v_mul_f32_e32 v1, v1, v16
	v_mul_f32_e32 v12, v64, v12
	v_mul_f32_e32 v13, v65, v13
	v_bfe_u32 v17, v12, 16, 1
	v_add3_u32 v12, v12, v17, s60
	v_bfe_u32 v17, v13, 16, 1
	v_lshrrev_b32_e32 v12, 16, v12
	v_add3_u32 v13, v13, v17, s60
	v_and_or_b32 v12, v13, s61, v12
	v_mul_f32_e32 v13, v14, v16
	v_mul_f32_e32 v13, v66, v13
	v_mul_f32_e32 v14, v15, v16
	v_mul_f32_e32 v14, v67, v14
	v_bfe_u32 v15, v13, 16, 1
	v_add3_u32 v13, v13, v15, s60
	v_bfe_u32 v15, v14, 16, 1
	v_lshrrev_b32_e32 v13, 16, v13
	v_add3_u32 v14, v14, v15, s60
	v_and_or_b32 v13, v14, s61, v13
	flat_store_dwordx2 v[28:29], v[12:13] offset:2048
	v_mul_f32_e32 v8, v68, v8
	v_mul_f32_e32 v9, v69, v9
	v_bfe_u32 v12, v8, 16, 1
	v_add3_u32 v8, v8, v12, s60
	v_bfe_u32 v12, v9, 16, 1
	v_lshrrev_b32_e32 v8, 16, v8
	v_add3_u32 v9, v9, v12, s60
	v_and_or_b32 v8, v9, s61, v8
	v_mul_f32_e32 v9, v10, v16
	v_mul_f32_e32 v9, v70, v9
	v_mul_f32_e32 v10, v11, v16
	v_mul_f32_e32 v10, v71, v10
	v_bfe_u32 v11, v9, 16, 1
	v_add3_u32 v9, v9, v11, s60
	v_bfe_u32 v11, v10, 16, 1
	v_lshrrev_b32_e32 v9, 16, v9
	v_add3_u32 v10, v10, v11, s60
	v_and_or_b32 v9, v10, s61, v9
	flat_store_dwordx2 v[28:29], v[8:9] offset:2560
	v_mul_f32_e32 v4, v72, v4
	v_mul_f32_e32 v5, v73, v5
	v_bfe_u32 v8, v4, 16, 1
	v_add3_u32 v4, v4, v8, s60
	v_bfe_u32 v8, v5, 16, 1
	v_lshrrev_b32_e32 v4, 16, v4
	v_add3_u32 v5, v5, v8, s60
	v_and_or_b32 v4, v5, s61, v4
	v_mul_f32_e32 v5, v6, v16
	v_mul_f32_e32 v5, v74, v5
	v_mul_f32_e32 v6, v7, v16
	v_mul_f32_e32 v6, v75, v6
	v_bfe_u32 v7, v5, 16, 1
	v_add3_u32 v5, v5, v7, s60
	v_bfe_u32 v7, v6, 16, 1
	v_lshrrev_b32_e32 v5, 16, v5
	v_add3_u32 v6, v6, v7, s60
	v_and_or_b32 v5, v6, s61, v5
	flat_store_dwordx2 v[28:29], v[4:5] offset:3072
	v_mul_f32_e32 v0, v0, v76
	v_mul_f32_e32 v1, v1, v77
	v_bfe_u32 v4, v0, 16, 1
	v_add3_u32 v0, v0, v4, s60
	v_bfe_u32 v4, v1, 16, 1
	v_lshrrev_b32_e32 v0, 16, v0
	v_add3_u32 v1, v1, v4, s60
	v_and_or_b32 v0, v1, s61, v0
	v_mul_f32_e32 v1, v2, v16
	v_mul_f32_e32 v1, v1, v78
	v_mul_f32_e32 v2, v3, v16
	v_mul_f32_e32 v2, v2, v79
	v_bfe_u32 v3, v1, 16, 1
	v_add3_u32 v1, v1, v3, s60
	v_bfe_u32 v3, v2, 16, 1
	v_lshrrev_b32_e32 v1, 16, v1
	v_add3_u32 v2, v2, v3, s60
	v_and_or_b32 v1, v2, s61, v1
	flat_store_dwordx2 v[28:29], v[0:1] offset:3584
	s_cbranch_scc0 .LBB0_183
